# attention: a wave whose 32 rows all have tail sum >= 128 computes one more tile (P exactly 0) and then skips the remaining tiles' VALU/MFMA work (exact)
# speedup vs baseline: 1.0061x; 1.0011x over previous
; __device__ __forceinline__ int tid_of(int wave) { return wave * 64 + lane_id(); }
; #define LAS __attribute__((address_space(3)))
; #define tid tid_of(wave)
; #define lane lane_id()
; __device__ __forceinline__ void attn_unit(LAS unsigned char* lds, const int wid, int b, int h, int qb, const bf16_t* __restrict__ Q, const bf16_t* __restrict__ K,
;                                           const bf16_t* __restrict__ V, const bf16_t* __restrict__ ZS, bf16_t* __restrict__ OG) {
;     const int tid = tid_of(wid), lane = tid & 63, r32 = lane & 31, hi = lane >> 5;
;     const size_t tok0 = (size_t)b * SEQ;
;     const int q0 = qb * 256, qw0 = q0 + 32 * wid, qabs = qw0 + r32;
;     bf16x8 qf[8];
;     { const bf16_t* qp = Q + (tok0 + qabs) * DM + h * HD + 8 * hi;
; #pragma unroll
;       for (int d0 = 0; d0 < 8; ++d0) qf[d0] = *(const bf16x8*)(qp + 16 * d0); }
;     f32x16 o[4];
; #pragma unroll
;     for (int c = 0; c < 4; ++c)
; #pragma unroll
;         for (int r = 0; r < 16; ++r) o[c][r] = 0.f;
;     bf16x8 pa[4];
; #pragma unroll
;     for (int s = 0; s < 4; ++s) pa[s] = (bf16x8){0, 0, 0, 0, 0, 0, 0, 0};
;     float carry = 0.f;
;     const int NT = (q0 + 256) / 64;
;     const int srow = tid >> 4, sch = (tid & 15) ^ (((srow & 3) << 2) | ((srow >> 2) & 3));
;     const bf16_t* kg = K + (tok0 + srow) * DM + h * HD + sch * 8;
;     const bf16_t* vg = V + (tok0 + srow) * DM + h * HD + sch * 8;
;     LAS unsigned char* ldsw = lds + wid * 1024;
;     ...
;     ATT_STAGE(NT - 1, 0, 32768);
;     asm volatile("s_waitcnt vmcnt(0)" ::: "memory");
;     __syncthreads();
;     unsigned koff[8];
; #pragma unroll
;     for (int d0 = 0; d0 < 8; ++d0) koff[d0] = off_b(r32, 2 * d0 + hi);
;     const unsigned qa = (lane & 15) >> 2, blk = (lane >> 4) & 1, pp = lane & 3;
;     unsigned vbase[2], vcq[4];
; #pragma unroll
;     for (int t = 0; t < 2; ++t) vbase[t] = 256u * (8 * t + 4 * hi + qa) + 16u * ((2 * blk + (pp >> 1)) ^ ((2 * t + hi) & 3)) + 8u * (pp & 1);
; #pragma unroll
;     for (int c = 0; c < 4; ++c) vcq[c] = 64u * ((unsigned)c ^ qa);
;     int kcur = 0, vprev = 2, vcur = 0, vnext = 1;
.LBB0_594:
	s_ashr_i32 s4, s2, 7
	s_ashr_i32 s5, s4, 31
	s_lshl_b64 s[50:51], s[4:5], 12
	s_lshl_b32 s4, s2, 8
	s_and_b32 s63, s4, 0x700
	s_add_i32 s64, s63, s54
	v_or_b32_e32 v144, s64, v178
	v_lshl_add_u64 v[0:1], s[50:51], 0, v[144:145]
	s_lshl_b32 s4, s2, 4
	v_lshlrev_b64 v[0:1], 12, v[0:1]
	s_and_b32 s62, s4, 0x780
	v_lshl_add_u64 v[0:1], s[92:93], 0, v[0:1]
	s_lshl_b32 s42, s62, 1
	v_lshl_add_u64 v[0:1], v[0:1], 0, s[42:43]
	v_lshl_add_u64 v[0:1], v[0:1], 0, v[150:151]
	global_load_dwordx4 v[96:99], v[0:1], off
	global_load_dwordx4 v[100:103], v[0:1], off offset:32
	global_load_dwordx4 v[104:107], v[0:1], off offset:64
	global_load_dwordx4 v[108:111], v[0:1], off offset:96
	global_load_dwordx4 v[112:115], v[0:1], off offset:128
	global_load_dwordx4 v[116:119], v[0:1], off offset:160
	global_load_dwordx4 v[120:123], v[0:1], off offset:192
	global_load_dwordx4 v[124:127], v[0:1], off offset:224
	v_lshl_add_u64 v[0:1], s[50:51], 0, v[146:147]
	v_readlane_b32 s6, v248, 27
	s_add_i32 s4, s63, 0x100
	v_lshlrev_b64 v[0:1], 12, v[0:1]
	v_readlane_b32 s7, v248, 28
	s_lshr_b32 s4, s4, 6
	v_lshl_add_u64 v[2:3], s[44:45], 0, v[0:1]
	v_lshl_add_u64 v[0:1], s[6:7], 0, v[0:1]
	v_lshl_add_u64 v[2:3], v[2:3], 0, s[42:43]
	v_lshl_add_u64 v[0:1], v[0:1], 0, s[42:43]
	s_add_i32 s42, s4, -1
	v_lshl_add_u64 v[154:155], v[2:3], 0, v[152:153]
	s_lshl_b64 s[4:5], s[42:43], 18
	s_mov_b32 m0, s55
	v_lshl_add_u64 v[156:157], v[0:1], 0, v[152:153]
	v_lshl_add_u64 v[0:1], v[154:155], 0, s[4:5]
	global_load_lds_dwordx4 v[0:1], off
	v_lshl_add_u64 v[0:1], v[0:1], 0, s[48:49]
	s_mov_b32 m0, s59
	v_mov_b32_e32 v32, v145
	global_load_lds_dwordx4 v[0:1], off
	v_lshl_add_u64 v[0:1], v[156:157], 0, s[4:5]
	s_mov_b32 m0, s60
	s_bfe_u32 s4, s57, 0x30008
	global_load_lds_dwordx4 v[0:1], off
	v_lshl_add_u64 v[0:1], v[0:1], 0, s[48:49]
	s_mov_b32 m0, s61
	v_mov_b32_e32 v33, v145
	global_load_lds_dwordx4 v[0:1], off
	s_waitcnt vmcnt(0)
	v_mov_b32_e32 v46, v145
	v_mov_b32_e32 v47, v145
	s_lshl_b32 s5, s4, 2
	s_lshl_b32 s4, s4, 8
	v_mov_b32_e32 v34, v145
	v_mov_b32_e32 v35, v145
	v_mov_b32_e32 v36, v145
	v_mov_b32_e32 v37, v145
	v_mov_b32_e32 v38, v145
	v_mov_b32_e32 v39, v145
	v_mov_b32_e32 v40, v145
	v_mov_b32_e32 v41, v145
	v_mov_b32_e32 v42, v145
	v_mov_b32_e32 v43, v145
	v_mov_b32_e32 v44, v145
	v_mov_b32_e32 v45, v145
	v_mov_b64_e32 v[62:63], v[46:47]
	v_mov_b64_e32 v[0:1], v[32:33]
	v_mov_b64_e32 v[16:17], v[32:33]
	s_or_b32 s42, s5, 2
	s_or_b32 s65, s4, 0xc0
	s_or_b32 s66, s64, 31
	s_mov_b64 s[4:5], 0
	v_mov_b64_e32 v[60:61], v[44:45]
	v_mov_b64_e32 v[58:59], v[42:43]
	v_mov_b64_e32 v[56:57], v[40:41]
	v_mov_b64_e32 v[54:55], v[38:39]
	v_mov_b64_e32 v[52:53], v[36:37]
	v_mov_b64_e32 v[50:51], v[34:35]
	v_mov_b64_e32 v[48:49], v[32:33]
	v_mov_b64_e32 v[2:3], v[34:35]
	v_mov_b64_e32 v[4:5], v[36:37]
	v_mov_b64_e32 v[6:7], v[38:39]
	v_mov_b64_e32 v[8:9], v[40:41]
	v_mov_b64_e32 v[10:11], v[42:43]
	v_mov_b64_e32 v[12:13], v[44:45]
	v_mov_b64_e32 v[14:15], v[46:47]
	v_mov_b64_e32 v[18:19], v[34:35]
	v_mov_b64_e32 v[20:21], v[36:37]
	v_mov_b64_e32 v[22:23], v[38:39]
	v_mov_b64_e32 v[24:25], v[40:41]
	v_mov_b64_e32 v[26:27], v[42:43]
	v_mov_b64_e32 v[28:29], v[44:45]
	v_mov_b64_e32 v[30:31], v[46:47]
	s_mov_b32 s67, s43
	s_mov_b32 s74, 0
	s_mov_b32 s6, 2
	s_mov_b32 s71, s43
	s_mov_b32 s72, 1
	v_mov_b32_e32 v158, 0
	v_mov_b32_e32 v140, 0
	v_mov_b32_e32 v141, v145
	v_mov_b32_e32 v142, v145
	v_mov_b32_e32 v143, v145
	v_mov_b32_e32 v136, 0
	v_mov_b32_e32 v137, v145
	v_mov_b32_e32 v138, v145
	v_mov_b32_e32 v139, v145
	v_mov_b32_e32 v132, 0
	v_mov_b32_e32 v133, v145
	v_mov_b32_e32 v134, v145
	v_mov_b32_e32 v135, v145
	v_mov_b32_e32 v128, 0
	v_mov_b32_e32 v129, v145
	v_mov_b32_e32 v130, v145
	v_mov_b32_e32 v131, v145
	s_waitcnt vmcnt(0) lgkmcnt(0)
	s_barrier
	s_mov_b32 s73, s6
	s_cmp_lg_u32 s65, 0
	s_mov_b64 s[6:7], -1
	s_cbranch_scc0 .LBB0_596

; #define LAS __attribute__((address_space(3)))
; #define ATT_SB() do {} while (0)
; #define ATT_SB() do {} while (0)
; #define ATT_SB() __builtin_amdgcn_sched_barrier(0)
; #define ATT_PV(f) do { if (DO_PV) { o[(f) >> 2] = __builtin_amdgcn_mfma_f32_32x32x16_bf16(pa[(f) & 3], vf[f], o[(f) >> 2], 0, 0, 0); if ((f) + 4 < 16) ATT_VLD((f) + 4); } } while (0)
; #define ATT_EXP8(i) do { _Pragma("unroll") for (int r_ = 0; r_ < 8; ++r_) p[(i) >> 1][8 * ((i) & 1) + r_] = __builtin_amdgcn_exp2f(fminf(p[(i) >> 1][8 * ((i) & 1) + r_], 30.f)); } while (0)
; template <bool DO_PV> ...
;     ...
;     {
;         bf16x8 ka[8], kc[8];
; #pragma unroll
;         for (int d0 = 0; d0 < 8; ++d0) { ka[d0] = *(const LAS bf16x8*)(kb + koff[d0]); kc[d0] = *(const LAS bf16x8*)(kb + 8192 + koff[d0]); }
;         ATT_SB();
; #pragma unroll
;         for (int d0 = 0; d0 < 8; ++d0) {
;             p[0] = __builtin_amdgcn_mfma_f32_32x32x16_bf16(ka[d0], qf[d0], p[0], 0, 0, 0);
;             p[1] = __builtin_amdgcn_mfma_f32_32x32x16_bf16(kc[d0], qf[d0], p[1], 0, 0, 0);
;         }
;     }
;     ATT_SB();
;     const bool need_mask = (k0 + 63 >= qw0);
;     float L[8], T[8];
;     ATT_PV(0); ATT_EXP8(0); ATT_SB();
;     ATT_PV(1); ATT_EXP8(1); ATT_SB();
;     ATT_PV(2); ATT_EXP8(2); ATT_SB();
;     ATT_PV(3); ATT_EXP8(3); ATT_SB();
; __device__ __forceinline__ void attn_unit(LAS unsigned char* lds, const int wid, int b, int h, int qb, const bf16_t* __restrict__ Q, const bf16_t* __restrict__ K,
;                                           const bf16_t* __restrict__ V, const bf16_t* __restrict__ ZS, bf16_t* __restrict__ OG) {
;     ...
;         const bool valid = (k0 < qw0 + 31);
;         if (valid) {
;             if (prev_valid) attn_tile<true>(kb, vbp, qf, o, pa, carry, koff, vbase, vcq, k0, qw0, qabs, hi);
;             else            attn_tile<false>(kb, vbp, qf, o, pa, carry, koff, vbase, vcq, k0, qw0, qabs, hi);
.LBB0_598:
	s_cmp_lt_i32 s65, s66
	s_cselect_b64 s[52:53], -1, 0
	s_cmp_ge_i32 s65, s66
	s_cbranch_scc1 .LBB0_608
	s_cmp_ge_u32 s74, 2
	s_cbranch_scc1 .LBB0_608
	s_xor_b64 s[6:7], s[4:5], -1
	s_add_i32 s8, s8, 0
	s_mov_b64 s[4:5], -1
	s_and_b64 vcc, exec, s[6:7]
	v_add_u32_e32 v168, s8, v179
	v_add_u32_e32 v167, s8, v180
	v_add_u32_e32 v166, s8, v181
	v_add_u32_e32 v165, s8, v182
	v_add_u32_e32 v164, s8, v183
	v_add_u32_e32 v163, s8, v184
	v_add_u32_e32 v162, s8, v185
	v_add_u32_e32 v149, s8, v186
	s_cbranch_vccz .LBB0_603
	ds_read_b128 v[64:67], v168
	ds_read_b128 v[68:71], v168 offset:8192
	ds_read_b128 v[170:173], v167
	ds_read_b128 v[174:177], v167 offset:8192
	s_add_i32 s4, s65, 63
	s_cmp_lt_i32 s4, s64
	s_waitcnt lgkmcnt(0)
	v_mfma_f32_32x32x16_bf16 v[80:95], v[64:67], v[96:99], 0
	v_mfma_f32_32x32x16_bf16 v[80:95], v[170:173], v[100:103], v[80:95]
	ds_read_b128 v[170:173], v166
	ds_read_b128 v[196:199], v166 offset:8192
	v_mfma_f32_32x32x16_bf16 v[64:79], v[68:71], v[96:99], 0
	s_waitcnt lgkmcnt(0)
	v_mfma_f32_32x32x16_bf16 v[80:95], v[170:173], v[104:107], v[80:95]
	ds_read_b128 v[170:173], v165
	ds_read_b128 v[200:203], v165 offset:8192
	v_mfma_f32_32x32x16_bf16 v[64:79], v[174:177], v[100:103], v[64:79]
	s_waitcnt lgkmcnt(0)
	v_mfma_f32_32x32x16_bf16 v[80:95], v[170:173], v[108:111], v[80:95]
	ds_read_b128 v[170:173], v164
	ds_read_b128 v[204:207], v164 offset:8192
	v_mfma_f32_32x32x16_bf16 v[64:79], v[196:199], v[104:107], v[64:79]
	s_waitcnt lgkmcnt(0)
	v_mfma_f32_32x32x16_bf16 v[80:95], v[170:173], v[112:115], v[80:95]
	ds_read_b128 v[170:173], v163
	ds_read_b128 v[208:211], v163 offset:8192
	v_mfma_f32_32x32x16_bf16 v[64:79], v[200:203], v[108:111], v[64:79]
	s_waitcnt lgkmcnt(0)
	v_mfma_f32_32x32x16_bf16 v[80:95], v[170:173], v[116:119], v[80:95]
	ds_read_b128 v[170:173], v162
	ds_read_b128 v[212:215], v162 offset:8192
	v_mfma_f32_32x32x16_bf16 v[64:79], v[204:207], v[112:115], v[64:79]
	s_waitcnt lgkmcnt(0)
	v_mfma_f32_32x32x16_bf16 v[80:95], v[170:173], v[120:123], v[80:95]
	ds_read_b128 v[170:173], v149
	ds_read_b128 v[216:219], v149 offset:8192
	v_mfma_f32_32x32x16_bf16 v[64:79], v[208:211], v[116:119], v[64:79]
	s_waitcnt lgkmcnt(0)
	v_mfma_f32_32x32x16_bf16 v[80:95], v[170:173], v[124:127], v[80:95]
	v_mfma_f32_32x32x16_bf16 v[64:79], v[212:215], v[120:123], v[64:79]
	s_nop 10
	v_min_f32_e32 v81, 0x41f00000, v81
	v_exp_f32_e32 v160, v81
	v_min_f32_e32 v81, 0x41f00000, v82
	v_exp_f32_e32 v161, v81
	v_min_f32_e32 v81, 0x41f00000, v83
	v_mfma_f32_32x32x16_bf16 v[64:79], v[216:219], v[124:127], v[64:79]
	v_min_f32_e32 v83, 0x41f00000, v85
	v_min_f32_e32 v82, 0x41f00000, v84
	v_exp_f32_e32 v84, v83
	v_min_f32_e32 v83, 0x41f00000, v86
	v_exp_f32_e32 v85, v83
	v_min_f32_e32 v83, 0x41f00000, v87
	v_min_f32_e32 v87, 0x41f00000, v89
	v_min_f32_e32 v86, 0x41f00000, v88
	v_exp_f32_e32 v88, v87
	v_min_f32_e32 v87, 0x41f00000, v90
	v_exp_f32_e32 v89, v87
	v_min_f32_e32 v87, 0x41f00000, v91
	v_min_f32_e32 v91, 0x41f00000, v93
	v_min_f32_e32 v65, 0x41f00000, v65
	v_min_f32_e32 v90, 0x41f00000, v92
	v_exp_f32_e32 v92, v91
	v_min_f32_e32 v91, 0x41f00000, v94
	v_exp_f32_e32 v94, v65
	v_min_f32_e32 v65, 0x41f00000, v66
	v_exp_f32_e32 v93, v91
	v_min_f32_e32 v91, 0x41f00000, v95
	v_exp_f32_e32 v95, v65
	v_min_f32_e32 v65, 0x41f00000, v67
	v_min_f32_e32 v67, 0x41f00000, v69
	v_min_f32_e32 v66, 0x41f00000, v68
	v_exp_f32_e32 v68, v67
	v_min_f32_e32 v67, 0x41f00000, v70
	v_exp_f32_e32 v69, v67
	v_min_f32_e32 v67, 0x41f00000, v71
	v_min_f32_e32 v71, 0x41f00000, v73
	v_min_f32_e32 v70, 0x41f00000, v72
	v_exp_f32_e32 v72, v71
	v_min_f32_e32 v71, 0x41f00000, v74
	v_exp_f32_e32 v73, v71
	v_min_f32_e32 v71, 0x41f00000, v75
	v_min_f32_e32 v75, 0x41f00000, v77
	v_min_f32_e32 v74, 0x41f00000, v76
	v_exp_f32_e32 v76, v75
	v_min_f32_e32 v75, 0x41f00000, v78
	v_exp_f32_e32 v77, v75
	v_min_f32_e32 v80, 0x41f00000, v80
	v_min_f32_e32 v64, 0x41f00000, v64
	v_min_f32_e32 v75, 0x41f00000, v79
	v_exp_f32_e32 v80, v80
	v_exp_f32_e32 v81, v81
	v_exp_f32_e32 v82, v82
	v_exp_f32_e32 v83, v83
	v_exp_f32_e32 v86, v86
	v_exp_f32_e32 v87, v87
	v_exp_f32_e32 v90, v90
	v_exp_f32_e32 v91, v91
	v_exp_f32_e32 v64, v64
	v_exp_f32_e32 v65, v65
	v_exp_f32_e32 v66, v66
	v_exp_f32_e32 v67, v67
	v_exp_f32_e32 v70, v70
	v_exp_f32_e32 v71, v71
	v_exp_f32_e32 v74, v74
	v_exp_f32_e32 v75, v75
	s_cbranch_scc1 .LBB0_602
; __device__ __forceinline__ int crow(int r, int hi) { return (r & 3) + 8 * (r >> 2) + 4 * hi; }
; template <bool DO_PV> ...
;     ...
;     if (need_mask) {
; #pragma unroll
;         for (int ph = 0; ph < 2; ++ph)
; #pragma unroll
;             for (int r = 0; r < 16; ++r) { const int key = k0 + 32 * ph + crow(r, hi); if (key >= qabs) p[ph][r] = 0.f; }
;     }
	v_add_u32_e32 v78, s65, v187
	v_add_u32_e32 v79, 1, v78
	v_cmp_lt_i32_e32 vcc, v78, v144
	v_cmp_lt_i32_e64 s[4:5], v79, v144
	s_or_b64 vcc, s[4:5], vcc
	v_add_u32_e32 v79, 2, v78
	v_cndmask_b32_e32 v80, 0, v80, vcc
	v_cmp_lt_i32_e32 vcc, v79, v144
	v_add_u32_e32 v79, 3, v78
	v_cndmask_b32_e64 v160, 0, v160, s[4:5]
	v_cndmask_b32_e32 v161, 0, v161, vcc
	v_cmp_lt_i32_e32 vcc, v79, v144
	v_add_u32_e32 v79, 8, v78
	s_nop 0
	v_cndmask_b32_e32 v81, 0, v81, vcc
	v_cmp_lt_i32_e32 vcc, v79, v144
	v_add_u32_e32 v79, 9, v78
	s_nop 0
	v_cndmask_b32_e32 v82, 0, v82, vcc
	v_cmp_lt_i32_e32 vcc, v79, v144
	v_add_u32_e32 v79, 10, v78
	s_nop 0
	v_cndmask_b32_e32 v84, 0, v84, vcc
	v_cmp_lt_i32_e32 vcc, v79, v144
	v_add_u32_e32 v79, 11, v78
	s_nop 0
	v_cndmask_b32_e32 v85, 0, v85, vcc
	v_cmp_lt_i32_e32 vcc, v79, v144
	v_add_u32_e32 v79, 16, v78
	s_nop 0
	v_cndmask_b32_e32 v83, 0, v83, vcc
	v_cmp_lt_i32_e32 vcc, v79, v144
	v_add_u32_e32 v79, 17, v78
	s_nop 0
	v_cndmask_b32_e32 v86, 0, v86, vcc
	v_cmp_lt_i32_e32 vcc, v79, v144
	v_add_u32_e32 v79, 18, v78
	s_nop 0
	v_cndmask_b32_e32 v88, 0, v88, vcc
	v_cmp_lt_i32_e32 vcc, v79, v144
	v_add_u32_e32 v79, 19, v78
	s_nop 0
	v_cndmask_b32_e32 v89, 0, v89, vcc
	v_cmp_lt_i32_e32 vcc, v79, v144
	v_add_u32_e32 v79, 24, v78
	s_nop 0
	v_cndmask_b32_e32 v87, 0, v87, vcc
	v_cmp_lt_i32_e32 vcc, v79, v144
	v_add_u32_e32 v79, 25, v78
	s_nop 0
	v_cndmask_b32_e32 v90, 0, v90, vcc
	v_cmp_lt_i32_e32 vcc, v79, v144
	v_add_u32_e32 v79, 26, v78
	s_nop 0
	v_cndmask_b32_e32 v92, 0, v92, vcc
	v_cmp_lt_i32_e32 vcc, v79, v144
	v_add_u32_e32 v79, 27, v78
	s_nop 0
	v_cndmask_b32_e32 v93, 0, v93, vcc
	v_cmp_lt_i32_e32 vcc, v79, v144
	v_add_u32_e32 v79, 32, v78
	v_cmp_lt_i32_e64 s[4:5], v79, v144
	v_add_u32_e32 v79, 33, v78
	v_cmp_lt_i32_e64 s[6:7], v79, v144
	v_add_u32_e32 v79, 34, v78
	v_cmp_lt_i32_e64 s[8:9], v79, v144
	v_add_u32_e32 v79, 35, v78
	v_cmp_lt_i32_e64 s[10:11], v79, v144
	v_add_u32_e32 v79, 40, v78
	v_cmp_lt_i32_e64 s[12:13], v79, v144
	v_add_u32_e32 v79, 41, v78
	v_cmp_lt_i32_e64 s[14:15], v79, v144
	v_add_u32_e32 v79, 42, v78
	v_cmp_lt_i32_e64 s[16:17], v79, v144
	v_add_u32_e32 v79, 43, v78
	v_cmp_lt_i32_e64 s[18:19], v79, v144
	v_add_u32_e32 v79, 48, v78
	v_cmp_lt_i32_e64 s[20:21], v79, v144
	v_add_u32_e32 v79, 49, v78
	v_cmp_lt_i32_e64 s[22:23], v79, v144
	v_add_u32_e32 v79, 50, v78
	v_cmp_lt_i32_e64 s[24:25], v79, v144
	v_add_u32_e32 v79, 51, v78
	v_cmp_lt_i32_e64 s[26:27], v79, v144
	v_add_u32_e32 v79, 56, v78
	v_cmp_lt_i32_e64 s[28:29], v79, v144
	v_add_u32_e32 v79, 57, v78
	v_cmp_lt_i32_e64 s[30:31], v79, v144
	v_add_u32_e32 v79, 58, v78
	v_add_u32_e32 v78, 59, v78
	v_cmp_lt_i32_e64 s[34:35], v79, v144
	v_cmp_lt_i32_e64 s[36:37], v78, v144
	s_or_b64 s[34:35], s[36:37], s[34:35]
	s_or_b64 s[30:31], s[34:35], s[30:31]
	s_or_b64 s[28:29], s[30:31], s[28:29]
	s_or_b64 s[26:27], s[28:29], s[26:27]
	s_or_b64 s[24:25], s[26:27], s[24:25]
	s_or_b64 s[22:23], s[24:25], s[22:23]
	s_or_b64 s[20:21], s[22:23], s[20:21]
	s_or_b64 s[18:19], s[20:21], s[18:19]
	s_or_b64 s[16:17], s[18:19], s[16:17]
	s_or_b64 s[14:15], s[16:17], s[14:15]
	s_or_b64 s[12:13], s[14:15], s[12:13]
	s_or_b64 s[10:11], s[12:13], s[10:11]
	s_or_b64 s[8:9], s[10:11], s[8:9]
	s_or_b64 s[6:7], s[8:9], s[6:7]
	s_or_b64 s[4:5], s[6:7], s[4:5]
	s_or_b64 vcc, s[4:5], vcc
	v_cndmask_b32_e64 v75, 0, v75, s[36:37]
	v_cndmask_b32_e64 v77, 0, v77, s[34:35]
	v_cndmask_b32_e64 v76, 0, v76, s[30:31]
	v_cndmask_b32_e64 v74, 0, v74, s[28:29]
	v_cndmask_b32_e64 v71, 0, v71, s[26:27]
	v_cndmask_b32_e64 v73, 0, v73, s[24:25]
	v_cndmask_b32_e64 v72, 0, v72, s[22:23]
	v_cndmask_b32_e64 v70, 0, v70, s[20:21]
	v_cndmask_b32_e64 v67, 0, v67, s[18:19]
	v_cndmask_b32_e64 v69, 0, v69, s[16:17]
	v_cndmask_b32_e64 v68, 0, v68, s[14:15]
	v_cndmask_b32_e64 v66, 0, v66, s[12:13]
	v_cndmask_b32_e64 v65, 0, v65, s[10:11]
	v_cndmask_b32_e64 v95, 0, v95, s[8:9]
	v_cndmask_b32_e64 v94, 0, v94, s[6:7]
	v_cndmask_b32_e64 v64, 0, v64, s[4:5]
	v_cndmask_b32_e32 v91, 0, v91, vcc

; #define LAS __attribute__((address_space(3)))
; __device__ __forceinline__ s16x4 vtr(const LAS unsigned char* p) { return __builtin_bit_cast(s16x4, __builtin_amdgcn_ds_read_tr16_b64_v4i16((LAS s16x4*)p)); }
; __device__ __forceinline__ void attn_unit(LAS unsigned char* lds, const int wid, int b, int h, int qb, const bf16_t* __restrict__ Q, const bf16_t* __restrict__ K,
;                                           const bf16_t* __restrict__ V, const bf16_t* __restrict__ ZS, bf16_t* __restrict__ OG) {
;     ...
;         prev_valid = valid;
;         asm volatile("s_waitcnt vmcnt(0)" ::: "memory");
;         __syncthreads();
;         kcur ^= 1; { const int tmp = vprev; vprev = vcur; vcur = vnext; vnext = tmp; }
;     }
;     { const LAS unsigned char* vbp = lds + 32768 + vprev * 16384;
; #pragma unroll
;       for (int c = 0; c < 4; ++c)
; #pragma unroll
;           for (int s = 0; s < 4; ++s) {
;               const s16x4 lo = vtr(vbp + 4096 * s + vbase[0] + vcq[c]);
;               const s16x4 hh = vtr(vbp + 4096 * s + vbase[1] + vcq[c]);
;               const bf16x8 vfr = (bf16x8){lo[0], lo[1], lo[2], lo[3], hh[0], hh[1], hh[2], hh[3]};
;               o[c] = __builtin_amdgcn_mfma_f32_32x32x16_bf16(pa[s], vfr, o[c], 0, 0, 0);
;           } }
.LBB0_609:
	s_waitcnt vmcnt(0)
	s_xor_b32 s67, s67, 1
	s_add_i32 s42, s42, -1
	s_sub_i32 s65, s65, 64
	v_cmp_gt_f32_e32 vcc, 0x43000000, v158
	s_lshr_b32 s98, s54, 3
	s_lshl_b32 s99, s67, 5
	s_add_i32 s98, s98, s99
	s_add_i32 s98, s98, 0x24000
	s_cmp_lg_u64 vcc, 0
	s_cselect_b32 s99, 1, 0
	s_xor_b32 s75, s99, 1
	s_add_i32 s74, s74, s75
	v_mov_b32_e32 v80, s98
	v_mov_b32_e32 v81, s99
	s_mov_b64 s[100:101], exec
	s_mov_b64 exec, 1
	ds_write_b32 v80, v81
	s_mov_b64 exec, s[100:101]
	s_cmpk_lg_i32 s65, 0xffc0
	s_waitcnt vmcnt(0) lgkmcnt(0)
	s_barrier
	s_cbranch_scc0 .LBB0_611
	s_lshl_b32 s98, s67, 5
	s_add_i32 s98, s98, 0x24000
	v_mov_b32_e32 v80, s98
	ds_read_b128 v[84:87], v80
	ds_read_b128 v[88:91], v80 offset:16
	s_waitcnt lgkmcnt(0)
	v_or3_b32 v84, v84, v85, v86
	v_or3_b32 v88, v88, v89, v90
	v_or3_b32 v84, v84, v87, v91
	v_or_b32_e32 v84, v84, v88
	s_nop 0
	v_readfirstlane_b32 s99, v84
	s_cmp_eq_u32 s99, 0
	s_cbranch_scc1 .LBB0_611
	s_mov_b32 s6, s71
	s_mov_b32 s71, s72
	s_mov_b32 s72, s73
	s_mov_b64 s[4:5], s[52:53]
	s_mov_b32 s73, s6
	s_cmp_lg_u32 s65, 0
	s_mov_b64 s[6:7], -1
	s_cbranch_scc1 .LBB0_595
	s_branch .LBB0_596
.LBB0_611:
	s_lshl_b32 s4, s71, 14
	s_add_i32 s4, s4, 0
	v_add_u32_e32 v112, s4, v188
	v_add_u32_e32 v113, s4, v189
	v_add_u32_e32 v86, v112, v190
	v_add_u32_e32 v94, v113, v190
	ds_read_b64_tr_b16 v[82:83], v94 offset:34816
	ds_read_b64_tr_b16 v[80:81], v86 offset:32768
	ds_read_b64_tr_b16 v[84:85], v86 offset:36864
	ds_read_b64_tr_b16 v[88:89], v86 offset:40960
	ds_read_b64_tr_b16 v[92:93], v86 offset:45056
	ds_read_b64_tr_b16 v[86:87], v94 offset:38912
	ds_read_b64_tr_b16 v[90:91], v94 offset:43008
	ds_read_b64_tr_b16 v[94:95], v94 offset:47104
	s_waitcnt lgkmcnt(6)
	v_mfma_f32_32x32x16_bf16 v[32:47], v[64:67], v[80:83], v[32:47]
	v_add_u32_e32 v82, v112, v191
	v_add_u32_e32 v98, v113, v191
	v_add_u32_e32 v102, v112, v192
	v_add_u32_e32 v110, v113, v192
	v_mov_b32_e32 v144, v195
	s_add_u32 s4, s50, s64
	s_addc_u32 s5, s51, 0
	s_waitcnt lgkmcnt(2)
	v_mfma_f32_32x32x16_bf16 v[32:47], v[68:71], v[84:87], v[32:47]
	s_lshl_b64 s[4:5], s[4:5], 11
	s_xor_b32 s7, s63, 0xf00
	s_add_i32 s63, s7, s54
	s_lshl_b32 s42, s62, 1
	s_mov_b32 m0, s55
	s_mov_b32 s64, 1
	s_mov_b32 s6, 2
	s_waitcnt lgkmcnt(1)
	v_mfma_f32_32x32x16_bf16 v[32:47], v[72:75], v[88:91], v[32:47]
	ds_read_b64_tr_b16 v[80:81], v82 offset:32768
	ds_read_b64_tr_b16 v[84:85], v82 offset:36864
	ds_read_b64_tr_b16 v[88:89], v82 offset:40960
	ds_read_b64_tr_b16 v[96:97], v82 offset:45056
	s_or_b32 s65, s63, 31
	s_add_i32 s66, s7, 0xff
	s_mov_b32 s67, 0
	s_mov_b32 s74, 0
	s_mov_b32 s71, 0
	s_waitcnt lgkmcnt(4)
	v_mfma_f32_32x32x16_bf16 v[32:47], v[76:79], v[92:95], v[32:47]
	ds_read_b64_tr_b16 v[82:83], v98 offset:34816
	ds_read_b64_tr_b16 v[86:87], v98 offset:38912
	ds_read_b64_tr_b16 v[90:91], v98 offset:43008
	ds_read_b64_tr_b16 v[98:99], v98 offset:47104
	ds_read_b64_tr_b16 v[92:93], v102 offset:32768
	ds_read_b64_tr_b16 v[100:101], v102 offset:36864
	ds_read_b64_tr_b16 v[104:105], v102 offset:40960
	ds_read_b64_tr_b16 v[108:109], v102 offset:45056
	ds_read_b64_tr_b16 v[94:95], v110 offset:34816
	ds_read_b64_tr_b16 v[102:103], v110 offset:38912
	ds_read_b64_tr_b16 v[106:107], v110 offset:43008
	ds_read_b64_tr_b16 v[110:111], v110 offset:47104
	s_waitcnt lgkmcnt(11)
	v_mfma_f32_32x32x16_bf16 v[48:63], v[64:67], v[80:83], v[48:63]
	v_add_u32_e32 v80, v112, v193
	v_add_u32_e32 v81, v113, v193
	ds_read_b64_tr_b16 v[112:113], v80 offset:32768
	ds_read_b64_tr_b16 v[116:117], v80 offset:36864
	ds_read_b64_tr_b16 v[120:121], v80 offset:40960
	ds_read_b64_tr_b16 v[124:125], v80 offset:45056
	ds_read_b64_tr_b16 v[114:115], v81 offset:34816
	ds_read_b64_tr_b16 v[118:119], v81 offset:38912
	ds_read_b64_tr_b16 v[122:123], v81 offset:43008
	ds_read_b64_tr_b16 v[126:127], v81 offset:47104
	v_mov_b32_e32 v81, s5
	v_lshlrev_b32_e32 v80, 3, v144
	s_waitcnt lgkmcnt(14)
	v_mfma_f32_32x32x16_bf16 v[48:63], v[68:71], v[84:87], v[48:63]
	v_and_b32_e32 v149, 56, v80
	v_or_b32_e32 v80, s4, v149
	v_ashrrev_i32_e32 v132, 3, v144
	v_or_b32_e32 v80, s62, v80
	v_lshlrev_b64 v[134:135], 1, v[80:81]
	v_ashrrev_i32_e32 v133, 31, v132
	v_lshl_add_u64 v[80:81], s[46:47], 0, v[134:135]
	v_lshlrev_b64 v[136:137], 12, v[132:133]
	v_lshl_add_u64 v[82:83], v[80:81], 0, v[136:137]
	v_mfma_f32_32x32x16_bf16 v[48:63], v[72:75], v[88:91], v[48:63]
	global_load_dwordx4 v[88:91], v[82:83], off
	v_add_u32_e32 v138, 8, v132
	v_ashrrev_i32_e32 v139, 31, v138
	v_lshlrev_b64 v[140:141], 12, v[138:139]
	v_lshl_add_u64 v[84:85], v[80:81], 0, v[140:141]
	v_add_u32_e32 v142, 16, v132
	v_add_u32_e32 v160, 24, v132
	s_waitcnt lgkmcnt(11)
	v_mfma_f32_32x32x16_bf16 v[0:15], v[64:67], v[92:95], v[0:15]
	global_load_dwordx4 v[92:95], v[84:85], off
	v_ashrrev_i32_e32 v143, 31, v142
	v_ashrrev_i32_e32 v161, 31, v160
	v_lshlrev_b64 v[158:159], 12, v[142:143]
	v_lshlrev_b64 v[162:163], 12, v[160:161]
	v_lshl_add_u64 v[86:87], v[80:81], 0, v[158:159]
	v_lshl_add_u64 v[80:81], v[80:81], 0, v[162:163]
	s_waitcnt lgkmcnt(10)
	v_mfma_f32_32x32x16_bf16 v[0:15], v[68:71], v[100:103], v[0:15]
	v_and_b32_e32 v133, 31, v144
	v_lshlrev_b32_e32 v133, 2, v133
	v_readlane_b32 s4, v248, 25
	v_readlane_b32 s5, v248, 26
	v_mov_b32_e32 v143, 0
	v_mov_b32_e32 v139, 0
	v_mfma_f32_32x32x16_bf16 v[48:63], v[76:79], v[96:99], v[48:63]
	global_load_dwordx4 v[96:99], v[82:83], off offset:128
	s_waitcnt lgkmcnt(9)
	v_mfma_f32_32x32x16_bf16 v[0:15], v[72:75], v[104:107], v[0:15]
	global_load_dwordx4 v[100:103], v[84:85], off offset:128
	global_load_dwordx4 v[104:107], v[86:87], off
	s_nop 0
	global_load_dwordx4 v[84:87], v[86:87], off offset:128
	s_nop 0
	global_load_dwordx4 v[128:131], v[80:81], off
	s_nop 0
	global_load_dwordx4 v[80:83], v[80:81], off offset:128
	s_waitcnt lgkmcnt(8)
; __device__ __forceinline__ int lane_id() { return (int)__builtin_amdgcn_mbcnt_hi(~0u, __builtin_amdgcn_mbcnt_lo(~0u, 0u)); }
; #define LAS __attribute__((address_space(3)))
; __device__ __forceinline__ unsigned pk_bf16(float lo, float hi) { return pg8::cvt_pk_bf16(lo, hi); }
; __device__ __forceinline__ float bf_lo(unsigned w) { return __uint_as_float(w << 16); }
; __device__ __forceinline__ float bf_hi(unsigned w) { return __uint_as_float(w & 0xffff0000u); }
; __device__ __forceinline__ void attn_unit(LAS unsigned char* lds, const int wid, int b, int h, int qb, const bf16_t* __restrict__ Q, const bf16_t* __restrict__ K,
;                                           const bf16_t* __restrict__ V, const bf16_t* __restrict__ ZS, bf16_t* __restrict__ OG) {
;     ...
;     {
;         int lane_e = lane_id(); asm volatile("" : "+v"(lane_e));
;         const int r32e = lane_e & 31, hie = lane_e >> 5, rowq = lane_e >> 3, c8 = (lane_e & 7) * 8;
;         LAS float* stg = (LAS float*)(lds + 81920 + wid * 8192);
;         const size_t gbase = (tok0 + qw0) * DM + h * HD + c8;
;         u32x4 zv[2][4];
; #pragma unroll
;         for (int ps = 0; ps < 2; ++ps)
; #pragma unroll
;             for (int j = 0; j < 4; ++j) zv[ps][j] = *(const u32x4*)(ZS + gbase + (size_t)(8 * j + rowq) * DM + 64 * ps);
; #pragma unroll
;         for (int ps = 0; ps < 2; ++ps) {
; #pragma unroll
;             for (int r = 0; r < 16; ++r) {
;                 stg[crow(r, hie) * 64 + r32e] = o[2 * ps][r];
;                 stg[crow(r, hie) * 64 + 32 + r32e] = o[2 * ps + 1][r];
;             }
;             asm volatile("s_waitcnt lgkmcnt(0)" ::: "memory");
; #pragma unroll
;             for (int j = 0; j < 4; ++j) {
;                 const f32x4 oa = *(const LAS f32x4*)(stg + (8 * j + rowq) * 64 + c8), ob = *(const LAS f32x4*)(stg + (8 * j + rowq) * 64 + c8 + 4);
;                 const u32x4 z = zv[ps][j];
;                 u32x4 w; w.x = pk_bf16(oa[0] * bf_lo(z.x), oa[1] * bf_hi(z.x)); w.y = pk_bf16(oa[2] * bf_lo(z.y), oa[3] * bf_hi(z.y));
;                 w.z = pk_bf16(ob[0] * bf_lo(z.z), ob[1] * bf_hi(z.z)); w.w = pk_bf16(ob[2] * bf_lo(z.w), ob[3] * bf_hi(z.w));
;                 *(u32x4*)(OG + gbase + (size_t)(8 * j + rowq) * DM + 64 * ps) = w;
;             }
;             asm volatile("s_waitcnt lgkmcnt(0)" ::: "memory");
;         }
	v_mfma_f32_32x32x16_bf16 v[0:15], v[76:79], v[108:111], v[0:15]
	v_lshlrev_b32_e32 v110, 5, v144
	v_and_b32_e32 v110, 0xfffffc00, v110
	v_add3_u32 v110, s56, v133, v110
	ds_write2_b32 v110, v32, v48 offset1:32
	ds_write2_b32 v110, v33, v49 offset0:64 offset1:96
	ds_write2_b32 v110, v34, v50 offset0:128 offset1:160
	ds_write2_b32 v110, v35, v51 offset0:192 offset1:224
	v_add_u32_e32 v48, 0x800, v110
	v_add_u32_e32 v49, 0x1000, v110
	v_add_u32_e32 v50, 0x1800, v110
	v_lshl_add_u32 v108, v149, 2, s56
	ds_write2_b32 v48, v36, v52 offset1:32
	ds_write2_b32 v48, v37, v53 offset0:64 offset1:96
	ds_write2_b32 v48, v38, v54 offset0:128 offset1:160
	ds_write2_b32 v48, v39, v55 offset0:192 offset1:224
	ds_write2_b32 v49, v40, v56 offset1:32
	ds_write2_b32 v49, v41, v57 offset0:64 offset1:96
	ds_write2_b32 v49, v42, v58 offset0:128 offset1:160
	ds_write2_b32 v49, v43, v59 offset0:192 offset1:224
	ds_write2_b32 v50, v44, v60 offset1:32
	ds_write2_b32 v50, v45, v61 offset0:64 offset1:96
	ds_write2_b32 v50, v46, v62 offset0:128 offset1:160
	ds_write2_b32 v50, v47, v63 offset0:192 offset1:224
	v_lshl_add_u32 v109, v132, 8, v108
	s_waitcnt lgkmcnt(0)
	ds_read_b128 v[32:35], v109
	ds_read_b128 v[36:39], v109 offset:16
	v_lshl_add_u32 v51, v138, 8, v108
	v_lshl_add_u64 v[40:41], s[4:5], 0, v[134:135]
	s_waitcnt lgkmcnt(14)
	v_mfma_f32_32x32x16_bf16 v[16:31], v[64:67], v[112:115], v[16:31]
	v_lshl_add_u32 v52, v142, 8, v108
	v_lshl_add_u32 v53, v160, 8, v108
	v_or_b32_e32 v144, s63, v178
	v_mov_b32_e32 v149, v145
	s_add_i32 s4, s7, 0x100
	s_lshr_b32 s8, s4, 6
	v_mov_b32_e32 v142, 0
	v_mfma_f32_32x32x16_bf16 v[16:31], v[68:71], v[116:119], v[16:31]
	v_mov_b32_e32 v138, 0
	v_mov_b32_e32 v132, 0
	v_mov_b32_e32 v133, 0
	v_mov_b32_e32 v134, 0
	v_mov_b32_e32 v135, 0
	s_waitcnt vmcnt(7)
	v_lshlrev_b32_e32 v42, 16, v88
	s_waitcnt lgkmcnt(1)
	v_mul_f32_e32 v32, v32, v42
	v_and_b32_e32 v42, 0xffff0000, v88
	v_mul_f32_e32 v33, v33, v42
	v_cvt_pk_bf16_f32 v32, v32, v33
	v_lshlrev_b32_e32 v33, 16, v89
	v_mul_f32_e32 v33, v34, v33
	v_and_b32_e32 v34, 0xffff0000, v89
	v_mul_f32_e32 v34, v35, v34
	v_cvt_pk_bf16_f32 v33, v33, v34
	v_lshlrev_b32_e32 v34, 16, v90
	v_and_b32_e32 v35, 0xffff0000, v90
	s_waitcnt lgkmcnt(0)
	v_mul_f32_e32 v34, v36, v34
	v_mul_f32_e32 v35, v37, v35
	v_cvt_pk_bf16_f32 v34, v34, v35
	v_lshlrev_b32_e32 v35, 16, v91
	v_and_b32_e32 v36, 0xffff0000, v91
	v_mul_f32_e32 v35, v38, v35
	v_mul_f32_e32 v36, v39, v36
	v_cvt_pk_bf16_f32 v35, v35, v36
	ds_read_b128 v[36:39], v51
	v_lshl_add_u64 v[42:43], v[40:41], 0, v[136:137]
	s_waitcnt vmcnt(6)
	v_lshlrev_b32_e32 v44, 16, v92
	global_store_dwordx4 v[42:43], v[32:35], off sc1
	ds_read_b128 v[32:35], v51 offset:16
	s_waitcnt lgkmcnt(1)
	v_mul_f32_e32 v36, v36, v44
	v_and_b32_e32 v44, 0xffff0000, v92
	v_mul_f32_e32 v37, v37, v44
	v_cvt_pk_bf16_f32 v36, v36, v37
	v_lshlrev_b32_e32 v37, 16, v93
	v_mul_f32_e32 v37, v38, v37
	v_and_b32_e32 v38, 0xffff0000, v93
	v_mul_f32_e32 v38, v39, v38
	v_cvt_pk_bf16_f32 v37, v37, v38
	v_lshlrev_b32_e32 v38, 16, v94
	s_waitcnt lgkmcnt(0)
	v_mul_f32_e32 v32, v32, v38
	v_and_b32_e32 v38, 0xffff0000, v94
	v_mul_f32_e32 v33, v33, v38
	v_cvt_pk_bf16_f32 v38, v32, v33
	v_lshlrev_b32_e32 v32, 16, v95
	v_and_b32_e32 v33, 0xffff0000, v95
	v_mul_f32_e32 v32, v34, v32
	v_mul_f32_e32 v33, v35, v33
	v_cvt_pk_bf16_f32 v39, v32, v33
	ds_read_b128 v[32:35], v52
	v_lshl_add_u64 v[44:45], v[40:41], 0, v[140:141]
	s_waitcnt vmcnt(4)
	v_lshlrev_b32_e32 v46, 16, v104
	global_store_dwordx4 v[44:45], v[36:39], off sc1
	ds_read_b128 v[36:39], v52 offset:16
	s_waitcnt lgkmcnt(1)
	v_mul_f32_e32 v32, v32, v46
	v_and_b32_e32 v46, 0xffff0000, v104
	v_mul_f32_e32 v33, v33, v46
	v_cvt_pk_bf16_f32 v32, v32, v33
	v_lshlrev_b32_e32 v33, 16, v105
	v_mul_f32_e32 v33, v34, v33
	v_and_b32_e32 v34, 0xffff0000, v105
	v_mul_f32_e32 v34, v35, v34
	v_cvt_pk_bf16_f32 v33, v33, v34
	v_lshlrev_b32_e32 v34, 16, v106
	v_and_b32_e32 v35, 0xffff0000, v106
	s_waitcnt lgkmcnt(0)
	v_mul_f32_e32 v34, v36, v34
	v_mul_f32_e32 v35, v37, v35
	v_cvt_pk_bf16_f32 v34, v34, v35
	v_lshlrev_b32_e32 v35, 16, v107
	v_and_b32_e32 v36, 0xffff0000, v107
	v_mul_f32_e32 v35, v38, v35
	v_mul_f32_e32 v36, v39, v36
	v_cvt_pk_bf16_f32 v35, v35, v36
	ds_read_b128 v[36:39], v53
	v_mfma_f32_32x32x16_bf16 v[16:31], v[72:75], v[120:123], v[16:31]
	v_lshl_add_u64 v[46:47], v[40:41], 0, v[158:159]
	s_waitcnt vmcnt(3)
	v_lshlrev_b32_e32 v54, 16, v128
	global_store_dwordx4 v[46:47], v[32:35], off sc1
	ds_read_b128 v[32:35], v53 offset:16
	s_waitcnt lgkmcnt(1)
	v_mul_f32_e32 v36, v36, v54
	v_and_b32_e32 v54, 0xffff0000, v128
	v_mul_f32_e32 v37, v37, v54
	v_cvt_pk_bf16_f32 v36, v36, v37
	v_lshlrev_b32_e32 v37, 16, v129
	v_mul_f32_e32 v37, v38, v37
	v_and_b32_e32 v38, 0xffff0000, v129
	v_mfma_f32_32x32x16_bf16 v[16:31], v[76:79], v[124:127], v[16:31]
	v_mul_f32_e32 v38, v39, v38
	v_cvt_pk_bf16_f32 v37, v37, v38
	v_lshlrev_b32_e32 v38, 16, v130
	s_waitcnt lgkmcnt(0)
	v_mul_f32_e32 v32, v32, v38
	v_and_b32_e32 v38, 0xffff0000, v130
	v_mul_f32_e32 v33, v33, v38
	v_cvt_pk_bf16_f32 v38, v32, v33
	v_lshlrev_b32_e32 v32, 16, v131
	v_and_b32_e32 v33, 0xffff0000, v131
	v_mul_f32_e32 v32, v34, v32
	v_mul_f32_e32 v33, v35, v33
	v_cvt_pk_bf16_f32 v39, v32, v33
	v_lshl_add_u64 v[32:33], v[40:41], 0, v[162:163]
	global_store_dwordx4 v[32:33], v[36:39], off sc1
	s_waitcnt lgkmcnt(0)
; #define LAS __attribute__((address_space(3)))
; __device__ __forceinline__ unsigned pk_bf16(float lo, float hi) { return pg8::cvt_pk_bf16(lo, hi); }
; __device__ __forceinline__ float bf_lo(unsigned w) { return __uint_as_float(w << 16); }
; __device__ __forceinline__ float bf_hi(unsigned w) { return __uint_as_float(w & 0xffff0000u); }
; #define tid tid_of(wave)
; __device__ __forceinline__ void attn_unit(LAS unsigned char* lds, const int wid, int b, int h, int qb, const bf16_t* __restrict__ Q, const bf16_t* __restrict__ K,
;                                           const bf16_t* __restrict__ V, const bf16_t* __restrict__ ZS, bf16_t* __restrict__ OG) {
;     ...
;     const int q0 = qb * 256, qw0 = q0 + 32 * wid, qabs = qw0 + r32;
;     bf16x8 qf[8];
;     { const bf16_t* qp = Q + (tok0 + qabs) * DM + h * HD + 8 * hi;
; #pragma unroll
;       for (int d0 = 0; d0 < 8; ++d0) qf[d0] = *(const bf16x8*)(qp + 16 * d0); }
;     f32x16 o[4];
; #pragma unroll
;     for (int c = 0; c < 4; ++c)
; #pragma unroll
;         for (int r = 0; r < 16; ++r) o[c][r] = 0.f;
;     bf16x8 pa[4];
; #pragma unroll
;     for (int s = 0; s < 4; ++s) pa[s] = (bf16x8){0, 0, 0, 0, 0, 0, 0, 0};
;     float carry = 0.f;
;     const int NT = (q0 + 256) / 64;
;     const int srow = tid >> 4, sch = (tid & 15) ^ (((srow & 3) << 2) | ((srow >> 2) & 3));
;     const bf16_t* kg = K + (tok0 + srow) * DM + h * HD + sch * 8;
;     const bf16_t* vg = V + (tok0 + srow) * DM + h * HD + sch * 8;
;     LAS unsigned char* ldsw = lds + wid * 1024;
;     ...
;     ATT_STAGE(NT - 1, 0, 32768);
;     asm volatile("s_waitcnt vmcnt(0)" ::: "memory");
;     __syncthreads();
;     ...
; #pragma unroll
;             for (int j = 0; j < 4; ++j) {
;                 const f32x4 oa = *(const LAS f32x4*)(stg + (8 * j + rowq) * 64 + c8), ob = *(const LAS f32x4*)(stg + (8 * j + rowq) * 64 + c8 + 4);
;                 const u32x4 z = zv[ps][j];
;                 u32x4 w; w.x = pk_bf16(oa[0] * bf_lo(z.x), oa[1] * bf_hi(z.x)); w.y = pk_bf16(oa[2] * bf_lo(z.y), oa[3] * bf_hi(z.y));
;                 w.z = pk_bf16(ob[0] * bf_lo(z.z), ob[1] * bf_hi(z.z)); w.w = pk_bf16(ob[2] * bf_lo(z.w), ob[3] * bf_hi(z.w));
;                 *(u32x4*)(OG + gbase + (size_t)(8 * j + rowq) * DM + 64 * ps) = w;
;             }
;             asm volatile("s_waitcnt lgkmcnt(0)" ::: "memory");
;         }
;     }
;     __syncthreads();
	ds_write2_b32 v110, v0, v16 offset1:32
	ds_write2_b32 v110, v1, v17 offset0:64 offset1:96
	ds_write2_b32 v110, v2, v18 offset0:128 offset1:160
	ds_write2_b32 v110, v3, v19 offset0:192 offset1:224
	ds_write2_b32 v48, v4, v20 offset1:32
	ds_write2_b32 v48, v5, v21 offset0:64 offset1:96
	ds_write2_b32 v48, v6, v22 offset0:128 offset1:160
	ds_write2_b32 v48, v7, v23 offset0:192 offset1:224
	ds_write2_b32 v49, v8, v24 offset1:32
	ds_write2_b32 v49, v9, v25 offset0:64 offset1:96
	ds_write2_b32 v49, v10, v26 offset0:128 offset1:160
	ds_write2_b32 v49, v11, v27 offset0:192 offset1:224
	ds_write2_b32 v50, v12, v28 offset1:32
	ds_write2_b32 v50, v13, v29 offset0:64 offset1:96
	ds_write2_b32 v50, v14, v30 offset0:128 offset1:160
	ds_write2_b32 v50, v15, v31 offset0:192 offset1:224
	s_waitcnt lgkmcnt(0)
	ds_read_b128 v[0:3], v109
	ds_read_b128 v[4:7], v109 offset:16
	v_lshlrev_b32_e32 v8, 16, v96
	v_mov_b32_e32 v34, v145
	v_mov_b32_e32 v35, v145
	s_waitcnt lgkmcnt(1)
	v_mul_f32_e32 v0, v0, v8
	v_and_b32_e32 v8, 0xffff0000, v96
	v_mul_f32_e32 v1, v1, v8
	v_cvt_pk_bf16_f32 v0, v0, v1
	v_lshlrev_b32_e32 v1, 16, v97
	v_mul_f32_e32 v1, v2, v1
	v_and_b32_e32 v2, 0xffff0000, v97
	v_mul_f32_e32 v2, v3, v2
	v_cvt_pk_bf16_f32 v1, v1, v2
	v_lshlrev_b32_e32 v2, 16, v98
	v_and_b32_e32 v3, 0xffff0000, v98
	s_waitcnt lgkmcnt(0)
	v_mul_f32_e32 v2, v4, v2
	v_mul_f32_e32 v3, v5, v3
	v_cvt_pk_bf16_f32 v2, v2, v3
	v_lshlrev_b32_e32 v3, 16, v99
	v_and_b32_e32 v4, 0xffff0000, v99
	v_mul_f32_e32 v3, v6, v3
	v_mul_f32_e32 v4, v7, v4
	v_cvt_pk_bf16_f32 v3, v3, v4
	ds_read_b128 v[4:7], v51
	v_lshlrev_b32_e32 v8, 16, v100
	global_store_dwordx4 v[42:43], v[0:3], off offset:128 sc1
	ds_read_b128 v[0:3], v51 offset:16
	v_mov_b32_e32 v36, v145
	s_waitcnt lgkmcnt(1)
	v_mul_f32_e32 v4, v4, v8
	v_and_b32_e32 v8, 0xffff0000, v100
	v_mul_f32_e32 v5, v5, v8
	v_cvt_pk_bf16_f32 v4, v4, v5
	v_lshlrev_b32_e32 v5, 16, v101
	v_mul_f32_e32 v5, v6, v5
	v_and_b32_e32 v6, 0xffff0000, v101
	v_mul_f32_e32 v6, v7, v6
	v_cvt_pk_bf16_f32 v5, v5, v6
	v_lshlrev_b32_e32 v6, 16, v102
	s_waitcnt lgkmcnt(0)
	v_mul_f32_e32 v0, v0, v6
	v_and_b32_e32 v6, 0xffff0000, v102
	v_mul_f32_e32 v1, v1, v6
	v_cvt_pk_bf16_f32 v6, v0, v1
	v_lshlrev_b32_e32 v0, 16, v103
	v_and_b32_e32 v1, 0xffff0000, v103
	v_mul_f32_e32 v0, v2, v0
	v_mul_f32_e32 v1, v3, v1
	v_cvt_pk_bf16_f32 v7, v0, v1
	ds_read_b128 v[0:3], v52
	v_lshlrev_b32_e32 v8, 16, v84
	global_store_dwordx4 v[44:45], v[4:7], off offset:128 sc1
	ds_read_b128 v[4:7], v52 offset:16
	v_mov_b32_e32 v37, v145
	s_waitcnt lgkmcnt(1)
	v_mul_f32_e32 v0, v0, v8
	v_and_b32_e32 v8, 0xffff0000, v84
	v_mul_f32_e32 v1, v1, v8
	v_cvt_pk_bf16_f32 v0, v0, v1
	v_lshlrev_b32_e32 v1, 16, v85
	v_mul_f32_e32 v1, v2, v1
	v_and_b32_e32 v2, 0xffff0000, v85
	v_mul_f32_e32 v2, v3, v2
	v_cvt_pk_bf16_f32 v1, v1, v2
	v_lshlrev_b32_e32 v2, 16, v86
	v_and_b32_e32 v3, 0xffff0000, v86
	s_waitcnt lgkmcnt(0)
	v_mul_f32_e32 v2, v4, v2
	v_mul_f32_e32 v3, v5, v3
	v_cvt_pk_bf16_f32 v2, v2, v3
	v_lshlrev_b32_e32 v3, 16, v87
	v_and_b32_e32 v4, 0xffff0000, v87
	v_mul_f32_e32 v3, v6, v3
	v_mul_f32_e32 v4, v7, v4
	v_cvt_pk_bf16_f32 v3, v3, v4
	ds_read_b128 v[4:7], v53
	s_waitcnt vmcnt(6)
	v_lshlrev_b32_e32 v8, 16, v80
	global_store_dwordx4 v[46:47], v[0:3], off offset:128 sc1
	ds_read_b128 v[0:3], v53 offset:16
	v_mov_b32_e32 v46, v145
	s_waitcnt lgkmcnt(1)
	v_mul_f32_e32 v4, v4, v8
	v_and_b32_e32 v8, 0xffff0000, v80
	v_mul_f32_e32 v5, v5, v8
	v_cvt_pk_bf16_f32 v4, v4, v5
	v_lshlrev_b32_e32 v5, 16, v81
	v_mul_f32_e32 v5, v6, v5
	v_and_b32_e32 v6, 0xffff0000, v81
	v_mul_f32_e32 v6, v7, v6
	v_cvt_pk_bf16_f32 v5, v5, v6
	v_lshlrev_b32_e32 v6, 16, v82
	s_waitcnt lgkmcnt(0)
	v_mul_f32_e32 v0, v0, v6
	v_and_b32_e32 v6, 0xffff0000, v82
	v_mul_f32_e32 v1, v1, v6
	v_cvt_pk_bf16_f32 v6, v0, v1
	v_lshlrev_b32_e32 v0, 16, v83
	v_and_b32_e32 v1, 0xffff0000, v83
	v_mul_f32_e32 v0, v2, v0
	v_mul_f32_e32 v1, v3, v1
	v_cvt_pk_bf16_f32 v7, v0, v1
	v_lshl_add_u64 v[0:1], s[50:51], 0, v[144:145]
	v_lshlrev_b64 v[0:1], 12, v[0:1]
	v_lshl_add_u64 v[0:1], s[92:93], 0, v[0:1]
	v_lshl_add_u64 v[0:1], v[0:1], 0, s[42:43]
	global_store_dwordx4 v[32:33], v[4:7], off offset:128 sc1
	v_lshl_add_u64 v[0:1], v[0:1], 0, v[148:149]
	s_waitcnt lgkmcnt(0)
	s_barrier
	global_load_dwordx4 v[96:99], v[0:1], off
	global_load_dwordx4 v[100:103], v[0:1], off offset:32
	global_load_dwordx4 v[104:107], v[0:1], off offset:64
	global_load_dwordx4 v[108:111], v[0:1], off offset:96
	global_load_dwordx4 v[112:115], v[0:1], off offset:128
	global_load_dwordx4 v[116:119], v[0:1], off offset:160
	global_load_dwordx4 v[120:123], v[0:1], off offset:192
	global_load_dwordx4 v[124:127], v[0:1], off offset:224
	s_add_i32 s42, s8, -1
	s_lshl_b64 s[4:5], s[42:43], 18
	v_lshl_add_u64 v[0:1], v[154:155], 0, s[4:5]
	global_load_lds_dwordx4 v[0:1], off
	v_lshl_add_u64 v[0:1], v[0:1], 0, s[48:49]
	s_mov_b32 m0, s59
	v_mov_b32_e32 v32, v145
	global_load_lds_dwordx4 v[0:1], off
	v_lshl_add_u64 v[0:1], v[156:157], 0, s[4:5]
	s_mov_b32 m0, s60
	v_mov_b32_e32 v33, v145
	global_load_lds_dwordx4 v[0:1], off
	v_lshl_add_u64 v[0:1], v[0:1], 0, s[48:49]
	s_mov_b32 m0, s61
	v_mov_b32_e32 v47, v145
	global_load_lds_dwordx4 v[0:1], off
	s_waitcnt vmcnt(0)
	v_mov_b32_e32 v38, v145
	v_mov_b32_e32 v39, v145
	v_mov_b32_e32 v40, v145
	v_mov_b32_e32 v41, v145
	v_mov_b32_e32 v42, v145
	v_mov_b32_e32 v43, v145
	v_mov_b32_e32 v44, v145
	v_mov_b32_e32 v45, v145
	v_mov_b64_e32 v[62:63], v[46:47]
	v_mov_b64_e32 v[0:1], v[32:33]
	v_mov_b64_e32 v[16:17], v[32:33]
	s_add_i32 s42, s8, -2
	v_mov_b32_e32 v158, 0
	s_mov_b64 s[4:5], 0
	v_mov_b32_e32 v140, 0
	v_mov_b32_e32 v141, 0
	v_mov_b32_e32 v136, 0
	v_mov_b32_e32 v137, 0
	v_mov_b32_e32 v128, 0
	v_mov_b32_e32 v129, 0
	v_mov_b32_e32 v130, 0
	v_mov_b32_e32 v131, 0
	v_mov_b64_e32 v[60:61], v[44:45]
	v_mov_b64_e32 v[58:59], v[42:43]
	v_mov_b64_e32 v[56:57], v[40:41]
	v_mov_b64_e32 v[54:55], v[38:39]
	v_mov_b64_e32 v[52:53], v[36:37]
	v_mov_b64_e32 v[50:51], v[34:35]
	v_mov_b64_e32 v[48:49], v[32:33]
	v_mov_b64_e32 v[2:3], v[34:35]
	v_mov_b64_e32 v[4:5], v[36:37]
	v_mov_b64_e32 v[6:7], v[38:39]
	v_mov_b64_e32 v[8:9], v[40:41]
	v_mov_b64_e32 v[10:11], v[42:43]
	v_mov_b64_e32 v[12:13], v[44:45]
	v_mov_b64_e32 v[14:15], v[46:47]
	v_mov_b64_e32 v[18:19], v[34:35]
	v_mov_b64_e32 v[20:21], v[36:37]
	v_mov_b64_e32 v[22:23], v[38:39]
	v_mov_b64_e32 v[24:25], v[40:41]
	v_mov_b64_e32 v[26:27], v[42:43]
	v_mov_b64_e32 v[28:29], v[44:45]
	v_mov_b64_e32 v[30:31], v[46:47]
	s_waitcnt vmcnt(0) lgkmcnt(0)
	s_barrier
	s_mov_b32 s72, s6
	s_cmp_lg_u32 s42, -1
	s_mov_b64 s[6:7], -1
	s_cbranch_scc0 .LBB0_613

; #define LAS __attribute__((address_space(3)))
; #define ATT_SB() do {} while (0)
; #define ATT_SB() do {} while (0)
; #define ATT_SB() __builtin_amdgcn_sched_barrier(0)
; #define ATT_PV(f) do { if (DO_PV) { o[(f) >> 2] = __builtin_amdgcn_mfma_f32_32x32x16_bf16(pa[(f) & 3], vf[f], o[(f) >> 2], 0, 0, 0); if ((f) + 4 < 16) ATT_VLD((f) + 4); } } while (0)
; #define ATT_EXP8(i) do { _Pragma("unroll") for (int r_ = 0; r_ < 8; ++r_) p[(i) >> 1][8 * ((i) & 1) + r_] = __builtin_amdgcn_exp2f(fminf(p[(i) >> 1][8 * ((i) & 1) + r_], 30.f)); } while (0)
; template <bool DO_PV> ...
;     ...
;     {
;         bf16x8 ka[8], kc[8];
; #pragma unroll
;         for (int d0 = 0; d0 < 8; ++d0) { ka[d0] = *(const LAS bf16x8*)(kb + koff[d0]); kc[d0] = *(const LAS bf16x8*)(kb + 8192 + koff[d0]); }
;         ATT_SB();
; #pragma unroll
;         for (int d0 = 0; d0 < 8; ++d0) {
;             p[0] = __builtin_amdgcn_mfma_f32_32x32x16_bf16(ka[d0], qf[d0], p[0], 0, 0, 0);
;             p[1] = __builtin_amdgcn_mfma_f32_32x32x16_bf16(kc[d0], qf[d0], p[1], 0, 0, 0);
;         }
;     }
;     ATT_SB();
;     const bool need_mask = (k0 + 63 >= qw0);
;     float L[8], T[8];
;     ATT_PV(0); ATT_EXP8(0); ATT_SB();
;     ATT_PV(1); ATT_EXP8(1); ATT_SB();
;     ATT_PV(2); ATT_EXP8(2); ATT_SB();
;     ATT_PV(3); ATT_EXP8(3); ATT_SB();
; __device__ __forceinline__ void attn_unit(LAS unsigned char* lds, const int wid, int b, int h, int qb, const bf16_t* __restrict__ Q, const bf16_t* __restrict__ K,
;                                           const bf16_t* __restrict__ V, const bf16_t* __restrict__ ZS, bf16_t* __restrict__ OG) {
;     ...
;         const bool valid = (k0 < qw0 + 31);
;         if (valid) {
;             if (prev_valid) attn_tile<true>(kb, vbp, qf, o, pa, carry, koff, vbase, vcq, k0, qw0, qabs, hi);
;             else            attn_tile<false>(kb, vbp, qf, o, pa, carry, koff, vbase, vcq, k0, qw0, qabs, hi);
.LBB0_615:
	s_sub_i32 s6, s66, 63
	s_cmp_lt_i32 s6, s65
	s_cselect_b64 s[52:53], -1, 0
	s_cmp_ge_i32 s6, s65
	s_cbranch_scc1 .LBB0_625
	s_cmp_ge_u32 s74, 2
	s_cbranch_scc1 .LBB0_625
	s_xor_b64 s[6:7], s[4:5], -1
	s_add_i32 s8, s8, 0
	s_mov_b64 s[4:5], -1
	s_and_b64 vcc, exec, s[6:7]
	v_add_u32_e32 v168, s8, v179
	v_add_u32_e32 v167, s8, v180
	v_add_u32_e32 v166, s8, v181
	v_add_u32_e32 v165, s8, v182
	v_add_u32_e32 v164, s8, v183
	v_add_u32_e32 v163, s8, v184
	v_add_u32_e32 v162, s8, v185
	v_add_u32_e32 v149, s8, v186
	s_cbranch_vccz .LBB0_620
	ds_read_b128 v[64:67], v168
	ds_read_b128 v[68:71], v168 offset:8192
	ds_read_b128 v[170:173], v167
	ds_read_b128 v[174:177], v167 offset:8192
	s_cmp_lt_i32 s66, s63
	s_waitcnt lgkmcnt(0)
	v_mfma_f32_32x32x16_bf16 v[80:95], v[64:67], v[96:99], 0
	v_mfma_f32_32x32x16_bf16 v[80:95], v[170:173], v[100:103], v[80:95]
	ds_read_b128 v[170:173], v166
	ds_read_b128 v[196:199], v166 offset:8192
	v_mfma_f32_32x32x16_bf16 v[64:79], v[68:71], v[96:99], 0
	s_waitcnt lgkmcnt(0)
	v_mfma_f32_32x32x16_bf16 v[80:95], v[170:173], v[104:107], v[80:95]
	ds_read_b128 v[170:173], v165
	ds_read_b128 v[200:203], v165 offset:8192
	v_mfma_f32_32x32x16_bf16 v[64:79], v[174:177], v[100:103], v[64:79]
	s_waitcnt lgkmcnt(0)
	v_mfma_f32_32x32x16_bf16 v[80:95], v[170:173], v[108:111], v[80:95]
	ds_read_b128 v[170:173], v164
	ds_read_b128 v[204:207], v164 offset:8192
	v_mfma_f32_32x32x16_bf16 v[64:79], v[196:199], v[104:107], v[64:79]
	s_waitcnt lgkmcnt(0)
	v_mfma_f32_32x32x16_bf16 v[80:95], v[170:173], v[112:115], v[80:95]
	ds_read_b128 v[170:173], v163
	ds_read_b128 v[208:211], v163 offset:8192
	v_mfma_f32_32x32x16_bf16 v[64:79], v[200:203], v[108:111], v[64:79]
	s_waitcnt lgkmcnt(0)
	v_mfma_f32_32x32x16_bf16 v[80:95], v[170:173], v[116:119], v[80:95]
	ds_read_b128 v[170:173], v162
	ds_read_b128 v[212:215], v162 offset:8192
	v_mfma_f32_32x32x16_bf16 v[64:79], v[204:207], v[112:115], v[64:79]
	s_waitcnt lgkmcnt(0)
	v_mfma_f32_32x32x16_bf16 v[80:95], v[170:173], v[120:123], v[80:95]
	ds_read_b128 v[170:173], v149
	ds_read_b128 v[216:219], v149 offset:8192
	v_mfma_f32_32x32x16_bf16 v[64:79], v[208:211], v[116:119], v[64:79]
	s_waitcnt lgkmcnt(0)
	v_mfma_f32_32x32x16_bf16 v[80:95], v[170:173], v[124:127], v[80:95]
	v_mfma_f32_32x32x16_bf16 v[64:79], v[212:215], v[120:123], v[64:79]
	s_nop 10
	v_min_f32_e32 v81, 0x41f00000, v81
	v_exp_f32_e32 v160, v81
	v_min_f32_e32 v81, 0x41f00000, v82
	v_exp_f32_e32 v161, v81
	v_min_f32_e32 v81, 0x41f00000, v83
	v_mfma_f32_32x32x16_bf16 v[64:79], v[216:219], v[124:127], v[64:79]
	v_min_f32_e32 v83, 0x41f00000, v85
	v_min_f32_e32 v82, 0x41f00000, v84
	v_exp_f32_e32 v84, v83
	v_min_f32_e32 v83, 0x41f00000, v86
	v_exp_f32_e32 v85, v83
	v_min_f32_e32 v83, 0x41f00000, v87
	v_min_f32_e32 v87, 0x41f00000, v89
	v_min_f32_e32 v86, 0x41f00000, v88
	v_exp_f32_e32 v88, v87
	v_min_f32_e32 v87, 0x41f00000, v90
	v_exp_f32_e32 v89, v87
	v_min_f32_e32 v87, 0x41f00000, v91
	v_min_f32_e32 v91, 0x41f00000, v93
	v_min_f32_e32 v65, 0x41f00000, v65
	v_min_f32_e32 v90, 0x41f00000, v92
	v_exp_f32_e32 v92, v91
	v_min_f32_e32 v91, 0x41f00000, v94
	v_exp_f32_e32 v94, v65
	v_min_f32_e32 v65, 0x41f00000, v66
	v_exp_f32_e32 v93, v91
	v_min_f32_e32 v91, 0x41f00000, v95
	v_exp_f32_e32 v95, v65
	v_min_f32_e32 v65, 0x41f00000, v67
	v_min_f32_e32 v67, 0x41f00000, v69
	v_min_f32_e32 v66, 0x41f00000, v68
	v_exp_f32_e32 v68, v67
	v_min_f32_e32 v67, 0x41f00000, v70
	v_exp_f32_e32 v69, v67
	v_min_f32_e32 v67, 0x41f00000, v71
	v_min_f32_e32 v71, 0x41f00000, v73
	v_min_f32_e32 v70, 0x41f00000, v72
	v_exp_f32_e32 v72, v71
	v_min_f32_e32 v71, 0x41f00000, v74
	v_exp_f32_e32 v73, v71
	v_min_f32_e32 v71, 0x41f00000, v75
	v_min_f32_e32 v75, 0x41f00000, v77
	v_min_f32_e32 v74, 0x41f00000, v76
	v_exp_f32_e32 v76, v75
	v_min_f32_e32 v75, 0x41f00000, v78
	v_exp_f32_e32 v77, v75
	v_min_f32_e32 v80, 0x41f00000, v80
	v_min_f32_e32 v64, 0x41f00000, v64
	v_min_f32_e32 v75, 0x41f00000, v79
	v_exp_f32_e32 v80, v80
	v_exp_f32_e32 v81, v81
	v_exp_f32_e32 v82, v82
	v_exp_f32_e32 v83, v83
	v_exp_f32_e32 v86, v86
	v_exp_f32_e32 v87, v87
	v_exp_f32_e32 v90, v90
	v_exp_f32_e32 v91, v91
	v_exp_f32_e32 v64, v64
	v_exp_f32_e32 v65, v65
	v_exp_f32_e32 v66, v66
	v_exp_f32_e32 v67, v67
	v_exp_f32_e32 v70, v70
	v_exp_f32_e32 v71, v71
	v_exp_f32_e32 v74, v74
	v_exp_f32_e32 v75, v75
	s_cbranch_scc1 .LBB0_619
; __device__ __forceinline__ int crow(int r, int hi) { return (r & 3) + 8 * (r >> 2) + 4 * hi; }
; template <bool DO_PV> ...
;     ...
;     if (need_mask) {
; #pragma unroll
;         for (int ph = 0; ph < 2; ++ph)
; #pragma unroll
;             for (int r = 0; r < 16; ++r) { const int key = k0 + 32 * ph + crow(r, hi); if (key >= qabs) p[ph][r] = 0.f; }
;     }
	v_add_u32_e32 v78, s66, v187
	v_subrev_u32_e32 v79, 63, v78
	v_cmp_lt_i32_e32 vcc, v79, v144
	v_subrev_u32_e32 v79, 62, v78
	v_cmp_lt_i32_e64 s[4:5], v79, v144
	s_or_b64 vcc, s[4:5], vcc
	v_subrev_u32_e32 v79, 61, v78
	v_cndmask_b32_e32 v80, 0, v80, vcc
	v_cmp_lt_i32_e32 vcc, v79, v144
	v_subrev_u32_e32 v79, 60, v78
	v_cndmask_b32_e64 v160, 0, v160, s[4:5]
	v_cndmask_b32_e32 v161, 0, v161, vcc
	v_cmp_lt_i32_e32 vcc, v79, v144
	v_subrev_u32_e32 v79, 55, v78
	s_nop 0
	v_cndmask_b32_e32 v81, 0, v81, vcc
	v_cmp_lt_i32_e32 vcc, v79, v144
	v_subrev_u32_e32 v79, 54, v78
	s_nop 0
	v_cndmask_b32_e32 v82, 0, v82, vcc
	v_cmp_lt_i32_e32 vcc, v79, v144
	v_subrev_u32_e32 v79, 53, v78
	s_nop 0
	v_cndmask_b32_e32 v84, 0, v84, vcc
	v_cmp_lt_i32_e32 vcc, v79, v144
	v_subrev_u32_e32 v79, 52, v78
	s_nop 0
	v_cndmask_b32_e32 v85, 0, v85, vcc
	v_cmp_lt_i32_e32 vcc, v79, v144
	v_subrev_u32_e32 v79, 47, v78
	s_nop 0
	v_cndmask_b32_e32 v83, 0, v83, vcc
	v_cmp_lt_i32_e32 vcc, v79, v144
	v_subrev_u32_e32 v79, 46, v78
	s_nop 0
	v_cndmask_b32_e32 v86, 0, v86, vcc
	v_cmp_lt_i32_e32 vcc, v79, v144
	v_subrev_u32_e32 v79, 45, v78
	s_nop 0
	v_cndmask_b32_e32 v88, 0, v88, vcc
	v_cmp_lt_i32_e32 vcc, v79, v144
	v_subrev_u32_e32 v79, 44, v78
	s_nop 0
	v_cndmask_b32_e32 v89, 0, v89, vcc
	v_cmp_lt_i32_e32 vcc, v79, v144
	v_subrev_u32_e32 v79, 39, v78
	s_nop 0
	v_cndmask_b32_e32 v87, 0, v87, vcc
	v_cmp_lt_i32_e32 vcc, v79, v144
	v_subrev_u32_e32 v79, 38, v78
	s_nop 0
	v_cndmask_b32_e32 v90, 0, v90, vcc
	v_cmp_lt_i32_e32 vcc, v79, v144
	v_subrev_u32_e32 v79, 37, v78
	s_nop 0
	v_cndmask_b32_e32 v92, 0, v92, vcc
	v_cmp_lt_i32_e32 vcc, v79, v144
	v_subrev_u32_e32 v79, 36, v78
	s_nop 0
	v_cndmask_b32_e32 v93, 0, v93, vcc
	v_cmp_lt_i32_e32 vcc, v79, v144
	v_subrev_u32_e32 v79, 31, v78
	v_cmp_lt_i32_e64 s[4:5], v79, v144
	v_subrev_u32_e32 v79, 30, v78
	v_cmp_lt_i32_e64 s[6:7], v79, v144
	v_subrev_u32_e32 v79, 29, v78
	v_cmp_lt_i32_e64 s[8:9], v79, v144
	v_subrev_u32_e32 v79, 28, v78
	v_cmp_lt_i32_e64 s[10:11], v79, v144
	v_subrev_u32_e32 v79, 23, v78
	v_cmp_lt_i32_e64 s[12:13], v79, v144
	v_subrev_u32_e32 v79, 22, v78
	v_cmp_lt_i32_e64 s[14:15], v79, v144
	v_subrev_u32_e32 v79, 21, v78
	v_cmp_lt_i32_e64 s[16:17], v79, v144
	v_subrev_u32_e32 v79, 20, v78
	v_cmp_lt_i32_e64 s[18:19], v79, v144
	v_add_u32_e32 v79, -15, v78
	v_cmp_lt_i32_e64 s[20:21], v79, v144
	v_add_u32_e32 v79, -14, v78
	v_cmp_lt_i32_e64 s[22:23], v79, v144
	v_add_u32_e32 v79, -13, v78
	v_cmp_lt_i32_e64 s[24:25], v79, v144
	v_add_u32_e32 v79, -12, v78
	v_cmp_lt_i32_e64 s[26:27], v79, v144
	v_add_u32_e32 v79, -7, v78
	v_cmp_lt_i32_e64 s[28:29], v79, v144
	v_add_u32_e32 v79, -6, v78
	v_cmp_lt_i32_e64 s[30:31], v79, v144
	v_add_u32_e32 v79, -5, v78
	v_add_u32_e32 v78, -4, v78
	v_cmp_lt_i32_e64 s[34:35], v79, v144
	v_cmp_lt_i32_e64 s[36:37], v78, v144
	s_or_b64 s[34:35], s[36:37], s[34:35]
	s_or_b64 s[30:31], s[34:35], s[30:31]
	s_or_b64 s[28:29], s[30:31], s[28:29]
	s_or_b64 s[26:27], s[28:29], s[26:27]
	s_or_b64 s[24:25], s[26:27], s[24:25]
	s_or_b64 s[22:23], s[24:25], s[22:23]
	s_or_b64 s[20:21], s[22:23], s[20:21]
	s_or_b64 s[18:19], s[20:21], s[18:19]
	s_or_b64 s[16:17], s[18:19], s[16:17]
	s_or_b64 s[14:15], s[16:17], s[14:15]
	s_or_b64 s[12:13], s[14:15], s[12:13]
	s_or_b64 s[10:11], s[12:13], s[10:11]
	s_or_b64 s[8:9], s[10:11], s[8:9]
	s_or_b64 s[6:7], s[8:9], s[6:7]
	s_or_b64 s[4:5], s[6:7], s[4:5]
	s_or_b64 vcc, s[4:5], vcc
	v_cndmask_b32_e64 v75, 0, v75, s[36:37]
	v_cndmask_b32_e64 v77, 0, v77, s[34:35]
	v_cndmask_b32_e64 v76, 0, v76, s[30:31]
	v_cndmask_b32_e64 v74, 0, v74, s[28:29]
	v_cndmask_b32_e64 v71, 0, v71, s[26:27]
	v_cndmask_b32_e64 v73, 0, v73, s[24:25]
	v_cndmask_b32_e64 v72, 0, v72, s[22:23]
	v_cndmask_b32_e64 v70, 0, v70, s[20:21]
	v_cndmask_b32_e64 v67, 0, v67, s[18:19]
	v_cndmask_b32_e64 v69, 0, v69, s[16:17]
	v_cndmask_b32_e64 v68, 0, v68, s[14:15]
	v_cndmask_b32_e64 v66, 0, v66, s[12:13]
	v_cndmask_b32_e64 v65, 0, v65, s[10:11]
	v_cndmask_b32_e64 v95, 0, v95, s[8:9]
	v_cndmask_b32_e64 v94, 0, v94, s[6:7]
	v_cndmask_b32_e64 v64, 0, v64, s[4:5]
	v_cndmask_b32_e32 v91, 0, v91, vcc

; __device__ __forceinline__ void attn_unit(LAS unsigned char* lds, const int wid, int b, int h, int qb, const bf16_t* __restrict__ Q, const bf16_t* __restrict__ K,
;                                           const bf16_t* __restrict__ V, const bf16_t* __restrict__ ZS, bf16_t* __restrict__ OG) {
;     ...
;         prev_valid = valid;
;         asm volatile("s_waitcnt vmcnt(0)" ::: "memory");
;         __syncthreads();
;         kcur ^= 1; { const int tmp = vprev; vprev = vcur; vcur = vnext; vnext = tmp; }
;     }
.LBB0_626:
	s_waitcnt vmcnt(0)
	s_xor_b32 s67, s67, 1
	s_add_i32 s42, s42, -1
	s_sub_i32 s66, s66, 64
	v_cmp_gt_f32_e32 vcc, 0x43000000, v158
	s_lshr_b32 s98, s54, 3
	s_lshl_b32 s99, s67, 5
	s_add_i32 s98, s98, s99
	s_add_i32 s98, s98, 0x24000
	s_cmp_lg_u64 vcc, 0
	s_cselect_b32 s99, 1, 0
	s_xor_b32 s75, s99, 1
	s_add_i32 s74, s74, s75
	v_mov_b32_e32 v80, s98
	v_mov_b32_e32 v81, s99
	s_mov_b64 s[100:101], exec
	s_mov_b64 exec, 1
	ds_write_b32 v80, v81
	s_mov_b64 exec, s[100:101]
	s_cmp_lg_u32 s42, -2
	s_waitcnt vmcnt(0) lgkmcnt(0)
	s_barrier
	s_cbranch_scc0 .LBB0_593
	s_lshl_b32 s98, s67, 5
	s_add_i32 s98, s98, 0x24000
	v_mov_b32_e32 v80, s98
	ds_read_b128 v[84:87], v80
	ds_read_b128 v[88:91], v80 offset:16
	s_waitcnt lgkmcnt(0)
	v_or3_b32 v84, v84, v85, v86
	v_or3_b32 v88, v88, v89, v90
	v_or3_b32 v84, v84, v87, v91
	v_or_b32_e32 v84, v84, v88
	s_nop 0
	v_readfirstlane_b32 s99, v84
	s_cmp_eq_u32 s99, 0
	s_cbranch_scc1 .LBB0_593
	s_mov_b32 s6, s71
	s_mov_b32 s71, s64
	s_mov_b32 s64, s72
	s_mov_b64 s[4:5], s[52:53]
	s_mov_b32 s72, s6
	s_cmp_lg_u32 s42, -1
	s_mov_b64 s[6:7], -1
	s_cbranch_scc1 .LBB0_612
	s_branch .LBB0_613
